# norm phase row stores written through (sc0 sc1): nothing left for the L2 writeback at the phase-end barrier
# speedup vs baseline: 1.0083x; 1.0014x over previous
; __device__ __forceinline__ unsigned pk2(float lo, float hi) { pk2_f2_t v = {lo, hi}; pk2_b2_t b = __builtin_convertvector(v, pk2_b2_t); return __builtin_bit_cast(unsigned, b); }
; __device__ __forceinline__ float wave_sum(float v) { v += lx<1>(v); v += lx<2>(v); v += lx<4>(v); v += lx<8>(v); v += lx<16>(v); return half_sum(v); }
; __device__ __forceinline__ void norm_mod_rows_b(const bf16* src, const float* gain, const float* sh, const float* sc, bf16* dst, int gw, int NGW, int lane) {
;     ...
;         __builtin_amdgcn_sched_barrier(0);
;         f32x4 x[8];
; #pragma unroll
;         for (int j = 0; j < 4; ++j) { x[2 * j] = (f32x4){lo16(cur[j].x), hi16(cur[j].x), lo16(cur[j].y), hi16(cur[j].y)}; x[2 * j + 1] = (f32x4){lo16(cur[j].z), hi16(cur[j].z), lo16(cur[j].w), hi16(cur[j].w)}; }
;         float ss = 0.f;
; #pragma unroll
;         for (int j = 0; j < 8; ++j) ss += (x[j].x * x[j].x + x[j].y * x[j].y) + (x[j].z * x[j].z + x[j].w * x[j].w);
;         const float rstd = rsqrtf(wave_sum(ss) * (1.f / DM) + 1e-6f);
;         v4u* o16 = (v4u*)(dst + (size_t)m * DM) + lane;
; #pragma unroll
;         for (int j = 0; j < 4; ++j) { const f32x4 y0 = x[2 * j] * rstd * A[2 * j] + B[2 * j], y1 = x[2 * j + 1] * rstd * A[2 * j + 1] + B[2 * j + 1];
;             v4u w; w.x = pk2(y0.x, y0.y); w.y = pk2(y0.z, y0.w); w.z = pk2(y1.x, y1.y); w.w = pk2(y1.z, y1.w); o16[64 * j] = w; }
; #pragma unroll
;         for (int j = 0; j < 4; ++j) cur[j] = nxt[j];
.LBB0_244:
	s_waitcnt vmcnt(0)
	v_lshlrev_b32_e32 v112, 16, v32
	v_and_b32_e32 v113, 0xffff0000, v32
	v_lshlrev_b32_e32 v32, 16, v33
	v_and_b32_e32 v33, 0xffff0000, v33
	v_lshlrev_b32_e32 v124, 16, v20
	v_and_b32_e32 v125, 0xffff0000, v20
	v_lshlrev_b32_e32 v126, 16, v21
	v_and_b32_e32 v127, 0xffff0000, v21
	v_mul_f32_e32 v20, v113, v113
	v_mul_f32_e32 v21, v33, v33
	v_lshlrev_b32_e32 v114, 16, v34
	v_and_b32_e32 v115, 0xffff0000, v34
	v_lshlrev_b32_e32 v34, 16, v35
	v_and_b32_e32 v35, 0xffff0000, v35
	v_fmac_f32_e32 v20, v112, v112
	v_fmac_f32_e32 v21, v32, v32
	v_lshlrev_b32_e32 v128, 16, v22
	v_and_b32_e32 v129, 0xffff0000, v22
	v_add_f32_e32 v20, v20, v21
	v_mul_f32_e32 v21, v115, v115
	v_mul_f32_e32 v22, v35, v35
	v_fmac_f32_e32 v21, v114, v114
	v_fmac_f32_e32 v22, v34, v34
	v_lshlrev_b32_e32 v116, 16, v28
	v_and_b32_e32 v117, 0xffff0000, v28
	v_lshlrev_b32_e32 v28, 16, v29
	v_and_b32_e32 v29, 0xffff0000, v29
	v_add_f32_e32 v21, v21, v22
	v_add_f32_e32 v20, v20, v21
	v_mul_f32_e32 v21, v117, v117
	v_mul_f32_e32 v22, v29, v29
	v_fmac_f32_e32 v21, v116, v116
	v_fmac_f32_e32 v22, v28, v28
	v_lshlrev_b32_e32 v118, 16, v30
	v_and_b32_e32 v119, 0xffff0000, v30
	v_lshlrev_b32_e32 v30, 16, v31
	v_and_b32_e32 v31, 0xffff0000, v31
	v_add_f32_e32 v21, v21, v22
	v_add_f32_e32 v20, v20, v21
	v_mul_f32_e32 v21, v119, v119
	v_mul_f32_e32 v22, v31, v31
	v_fmac_f32_e32 v21, v118, v118
	v_fmac_f32_e32 v22, v30, v30
	v_lshlrev_b32_e32 v120, 16, v24
	v_and_b32_e32 v121, 0xffff0000, v24
	v_lshlrev_b32_e32 v24, 16, v25
	v_and_b32_e32 v25, 0xffff0000, v25
	v_add_f32_e32 v21, v21, v22
	v_add_f32_e32 v20, v21, v20
	v_mul_f32_e32 v21, v121, v121
	v_mul_f32_e32 v22, v25, v25
	v_fmac_f32_e32 v21, v120, v120
	v_fmac_f32_e32 v22, v24, v24
	v_lshlrev_b32_e32 v122, 16, v26
	v_and_b32_e32 v123, 0xffff0000, v26
	v_lshlrev_b32_e32 v26, 16, v27
	v_and_b32_e32 v27, 0xffff0000, v27
	v_add_f32_e32 v21, v21, v22
	v_add_f32_e32 v20, v21, v20
	v_mul_f32_e32 v21, v123, v123
	v_mul_f32_e32 v22, v27, v27
	v_fmac_f32_e32 v21, v122, v122
	v_fmac_f32_e32 v22, v26, v26
	v_add_f32_e32 v21, v21, v22
	v_add_f32_e32 v20, v21, v20
	v_mul_f32_e32 v21, v125, v125
	v_mul_f32_e32 v22, v127, v127
	v_fmac_f32_e32 v21, v124, v124
	v_fmac_f32_e32 v22, v126, v126
	v_and_b32_e32 v131, 0xffff0000, v23
	v_add_f32_e32 v21, v21, v22
	v_lshlrev_b32_e32 v130, 16, v23
	v_add_f32_e32 v20, v21, v20
	v_mul_f32_e32 v21, v129, v129
	v_mul_f32_e32 v22, v131, v131
	v_fmac_f32_e32 v21, v128, v128
	v_fmac_f32_e32 v22, v130, v130
	v_add_f32_e32 v21, v21, v22
	v_add_f32_e32 v20, v21, v20
	ds_swizzle_b32 v21, v20 offset:swizzle(SWAP,1)
	s_mov_b32 s11, 0x800000
	s_waitcnt lgkmcnt(0)
	v_add_f32_e32 v20, v20, v21
	ds_swizzle_b32 v21, v20 offset:swizzle(SWAP,2)
	s_waitcnt lgkmcnt(0)
	v_add_f32_e32 v20, v20, v21
	ds_swizzle_b32 v21, v20 offset:swizzle(SWAP,4)
	s_waitcnt lgkmcnt(0)
	v_add_f32_e32 v20, v20, v21
	ds_swizzle_b32 v21, v20 offset:swizzle(SWAP,8)
	s_waitcnt lgkmcnt(0)
	v_add_f32_e32 v20, v20, v21
	ds_swizzle_b32 v21, v20 offset:swizzle(SWAP,16)
	s_waitcnt lgkmcnt(0)
	v_add_f32_e32 v20, v20, v21
	v_mov_b32_e32 v21, v20
	s_nop 1
	v_permlane32_swap_b32_e32 v20, v21
	v_add_f32_e32 v20, v20, v21
	v_fmamk_f32 v20, v20, 0x3a000000, v228
	v_mul_f32_e32 v21, 0x4b800000, v20
	v_cmp_gt_f32_e32 vcc, s11, v20
	s_nop 1
	v_cndmask_b32_e32 v20, v20, v21, vcc
	v_rsq_f32_e32 v20, v20
	s_nop 0
	v_mul_f32_e32 v21, 0x45800000, v20
	v_cndmask_b32_e32 v132, v20, v21, vcc
	v_pk_mul_f32 v[20:21], v[112:113], v[132:133] op_sel_hi:[1,0]
	v_pk_mul_f32 v[22:23], v[32:33], v[132:133] op_sel_hi:[1,0]
	v_pk_mul_f32 v[32:33], v[114:115], v[132:133] op_sel_hi:[1,0]
	v_pk_mul_f32 v[34:35], v[34:35], v[132:133] op_sel_hi:[1,0]
	v_pk_fma_f32 v[22:23], v[70:71], v[22:23], v[58:59]
	v_pk_fma_f32 v[20:21], v[68:69], v[20:21], v[56:57]
	v_pk_fma_f32 v[34:35], v[74:75], v[34:35], v[46:47]
	v_pk_fma_f32 v[32:33], v[72:73], v[32:33], v[44:45]
	v_cvt_pk_bf16_f32 v20, v20, v21
	v_cvt_pk_bf16_f32 v21, v22, v23
	v_cvt_pk_bf16_f32 v22, v32, v33
	v_cvt_pk_bf16_f32 v23, v34, v35
	flat_store_dwordx4 v[108:109], v[20:23] sc0 sc1
	v_pk_mul_f32 v[30:31], v[30:31], v[132:133] op_sel_hi:[1,0]
	v_pk_mul_f32 v[26:27], v[26:27], v[132:133] op_sel_hi:[1,0]
	v_pk_mul_f32 v[20:21], v[116:117], v[132:133] op_sel_hi:[1,0]
	v_pk_mul_f32 v[22:23], v[28:29], v[132:133] op_sel_hi:[1,0]
	v_pk_mul_f32 v[28:29], v[118:119], v[132:133] op_sel_hi:[1,0]
	v_pk_fma_f32 v[22:23], v[78:79], v[22:23], v[54:55]
	v_pk_fma_f32 v[20:21], v[76:77], v[20:21], v[52:53]
	v_pk_fma_f32 v[30:31], v[82:83], v[30:31], v[42:43]
	v_pk_fma_f32 v[28:29], v[80:81], v[28:29], v[40:41]
	v_cvt_pk_bf16_f32 v20, v20, v21
	v_cvt_pk_bf16_f32 v21, v22, v23
	v_cvt_pk_bf16_f32 v22, v28, v29
	v_cvt_pk_bf16_f32 v23, v30, v31
	flat_store_dwordx4 v[108:109], v[20:23] offset:1024 sc0 sc1
	v_pk_fma_f32 v[26:27], v[90:91], v[26:27], v[38:39]
	v_mov_b64_e32 v[34:35], v[6:7]
	v_pk_mul_f32 v[20:21], v[120:121], v[132:133] op_sel_hi:[1,0]
	v_pk_mul_f32 v[22:23], v[24:25], v[132:133] op_sel_hi:[1,0]
	v_pk_mul_f32 v[24:25], v[122:123], v[132:133] op_sel_hi:[1,0]
	v_pk_fma_f32 v[22:23], v[86:87], v[22:23], v[50:51]
	v_pk_fma_f32 v[20:21], v[84:85], v[20:21], v[48:49]
	v_pk_fma_f32 v[24:25], v[88:89], v[24:25], v[36:37]
	v_cvt_pk_bf16_f32 v20, v20, v21
	v_cvt_pk_bf16_f32 v21, v22, v23
	v_cvt_pk_bf16_f32 v22, v24, v25
	v_cvt_pk_bf16_f32 v23, v26, v27
	flat_store_dwordx4 v[108:109], v[20:23] offset:2048 sc0 sc1
	v_pk_mul_f32 v[24:25], v[128:129], v[132:133] op_sel_hi:[1,0]
	v_pk_mul_f32 v[26:27], v[130:131], v[132:133] op_sel_hi:[1,0]
	v_pk_mul_f32 v[20:21], v[124:125], v[132:133] op_sel_hi:[1,0]
	v_pk_mul_f32 v[22:23], v[126:127], v[132:133] op_sel_hi:[1,0]
	v_pk_fma_f32 v[20:21], v[92:93], v[20:21], v[64:65]
	v_pk_fma_f32 v[22:23], v[94:95], v[22:23], v[66:67]
	v_pk_fma_f32 v[26:27], v[98:99], v[26:27], v[62:63]
	v_pk_fma_f32 v[24:25], v[96:97], v[24:25], v[60:61]
	v_cvt_pk_bf16_f32 v20, v20, v21
	v_cvt_pk_bf16_f32 v21, v22, v23
	v_cvt_pk_bf16_f32 v22, v24, v25
	v_cvt_pk_bf16_f32 v23, v26, v27
	flat_store_dwordx4 v[108:109], v[20:23] offset:3072 sc0 sc1
	v_mov_b64_e32 v[30:31], v[10:11]
	v_mov_b64_e32 v[26:27], v[14:15]
	v_mov_b64_e32 v[22:23], v[18:19]
	v_lshl_add_u64 v[108:109], v[108:109], 0, s[20:21]
	s_andn2_b64 vcc, exec, s[24:25]
	v_mov_b64_e32 v[32:33], v[4:5]
	v_mov_b64_e32 v[28:29], v[8:9]
	v_mov_b64_e32 v[24:25], v[12:13]
	v_mov_b64_e32 v[20:21], v[16:17]
	s_cbranch_vccz .LBB0_247

; __device__ __forceinline__ unsigned pk2(float lo, float hi) { pk2_f2_t v = {lo, hi}; pk2_b2_t b = __builtin_convertvector(v, pk2_b2_t); return __builtin_bit_cast(unsigned, b); }
; __device__ __forceinline__ float wave_sum(float v) { v += lx<1>(v); v += lx<2>(v); v += lx<4>(v); v += lx<8>(v); v += lx<16>(v); return half_sum(v); }
; __device__ __forceinline__ void norm_mod_rows(const float* src, const float* gain, const float* sh, const float* sc, bf16* dst, int gw, int NGW, int lane) {
;     ...
;         __builtin_amdgcn_sched_barrier(0);
;         float ss = 0.f;
; #pragma unroll
;         for (int j = 0; j < 8; ++j) ss += (cur[j].x * cur[j].x + cur[j].y * cur[j].y) + (cur[j].z * cur[j].z + cur[j].w * cur[j].w);
;         const float rstd = rsqrtf(wave_sum(ss) * (1.f / DM) + 1e-6f);
;         v2u* o8 = (v2u*)(dst + (size_t)m * DM) + lane;
; #pragma unroll
;         for (int j = 0; j < 8; ++j) { const f32x4 y = cur[j] * rstd * A[j] + B[j]; v2u w; w.x = pk2(y.x, y.y); w.y = pk2(y.z, y.w); o8[64 * j] = w; }
; #pragma unroll
;         for (int j = 0; j < 8; ++j) cur[j] = nxt[j];
.LBB0_251:
	s_waitcnt vmcnt(0)
	v_mul_f32_e32 v148, v33, v33
	v_mul_f32_e32 v149, v35, v35
	v_fmac_f32_e32 v148, v32, v32
	v_fmac_f32_e32 v149, v34, v34
	v_add_f32_e32 v148, v148, v149
	v_mul_f32_e32 v149, v29, v29
	v_mul_f32_e32 v150, v31, v31
	v_fmac_f32_e32 v149, v28, v28
	v_fmac_f32_e32 v150, v30, v30
	v_add_f32_e32 v149, v149, v150
	v_add_f32_e32 v148, v148, v149
	v_mul_f32_e32 v149, v25, v25
	v_mul_f32_e32 v150, v27, v27
	v_fmac_f32_e32 v149, v24, v24
	v_fmac_f32_e32 v150, v26, v26
	v_add_f32_e32 v149, v149, v150
	v_add_f32_e32 v148, v149, v148
	v_mul_f32_e32 v149, v21, v21
	v_mul_f32_e32 v150, v23, v23
	v_fmac_f32_e32 v149, v20, v20
	v_fmac_f32_e32 v150, v22, v22
	v_add_f32_e32 v149, v149, v150
	v_add_f32_e32 v148, v149, v148
	v_mul_f32_e32 v149, v17, v17
	v_mul_f32_e32 v150, v19, v19
	v_fmac_f32_e32 v149, v16, v16
	v_fmac_f32_e32 v150, v18, v18
	v_add_f32_e32 v149, v149, v150
	v_add_f32_e32 v148, v149, v148
	v_mul_f32_e32 v149, v13, v13
	v_mul_f32_e32 v150, v15, v15
	v_fmac_f32_e32 v149, v12, v12
	v_fmac_f32_e32 v150, v14, v14
	v_add_f32_e32 v149, v149, v150
	v_add_f32_e32 v148, v149, v148
	v_mul_f32_e32 v149, v9, v9
	v_mul_f32_e32 v150, v11, v11
	v_fmac_f32_e32 v149, v8, v8
	v_fmac_f32_e32 v150, v10, v10
	v_add_f32_e32 v149, v149, v150
	v_add_f32_e32 v148, v149, v148
	v_mul_f32_e32 v149, v5, v5
	v_mul_f32_e32 v150, v7, v7
	v_fmac_f32_e32 v149, v4, v4
	v_fmac_f32_e32 v150, v6, v6
	v_add_f32_e32 v149, v149, v150
	v_add_f32_e32 v148, v149, v148
	ds_swizzle_b32 v149, v148 offset:swizzle(SWAP,1)
	s_mov_b32 s9, 0x800000
	s_waitcnt lgkmcnt(0)
	v_add_f32_e32 v148, v148, v149
	ds_swizzle_b32 v149, v148 offset:swizzle(SWAP,2)
	s_waitcnt lgkmcnt(0)
	v_add_f32_e32 v148, v148, v149
	ds_swizzle_b32 v149, v148 offset:swizzle(SWAP,4)
	s_waitcnt lgkmcnt(0)
	v_add_f32_e32 v148, v148, v149
	ds_swizzle_b32 v149, v148 offset:swizzle(SWAP,8)
	s_waitcnt lgkmcnt(0)
	v_add_f32_e32 v148, v148, v149
	ds_swizzle_b32 v149, v148 offset:swizzle(SWAP,16)
	s_waitcnt lgkmcnt(0)
	v_add_f32_e32 v148, v148, v149
	v_mov_b32_e32 v149, v148
	s_nop 1
	v_permlane32_swap_b32_e32 v148, v149
	v_add_f32_e32 v148, v148, v149
	v_fmamk_f32 v148, v148, 0x3a000000, v228
	v_mul_f32_e32 v149, 0x4b800000, v148
	v_cmp_gt_f32_e32 vcc, s9, v148
	s_nop 1
	v_cndmask_b32_e32 v148, v148, v149, vcc
	v_rsq_f32_e32 v148, v148
	s_nop 0
	v_mul_f32_e32 v149, 0x45800000, v148
	v_cndmask_b32_e32 v148, v148, v149, vcc
	v_pk_mul_f32 v[32:33], v[32:33], v[148:149] op_sel_hi:[1,0]
	v_pk_mul_f32 v[34:35], v[34:35], v[148:149] op_sel_hi:[1,0]
	v_pk_mul_f32 v[28:29], v[28:29], v[148:149] op_sel_hi:[1,0]
	v_pk_mul_f32 v[30:31], v[30:31], v[148:149] op_sel_hi:[1,0]
	v_pk_mul_f32 v[24:25], v[24:25], v[148:149] op_sel_hi:[1,0]
	v_pk_mul_f32 v[26:27], v[26:27], v[148:149] op_sel_hi:[1,0]
	v_pk_mul_f32 v[20:21], v[20:21], v[148:149] op_sel_hi:[1,0]
	v_pk_mul_f32 v[22:23], v[22:23], v[148:149] op_sel_hi:[1,0]
	v_pk_mul_f32 v[16:17], v[16:17], v[148:149] op_sel_hi:[1,0]
	v_pk_mul_f32 v[18:19], v[18:19], v[148:149] op_sel_hi:[1,0]
	v_pk_mul_f32 v[12:13], v[12:13], v[148:149] op_sel_hi:[1,0]
	v_pk_mul_f32 v[14:15], v[14:15], v[148:149] op_sel_hi:[1,0]
	v_pk_mul_f32 v[8:9], v[8:9], v[148:149] op_sel_hi:[1,0]
	v_pk_mul_f32 v[10:11], v[10:11], v[148:149] op_sel_hi:[1,0]
	v_pk_mul_f32 v[4:5], v[4:5], v[148:149] op_sel_hi:[1,0]
	v_pk_mul_f32 v[6:7], v[6:7], v[148:149] op_sel_hi:[1,0]
	v_pk_fma_f32 v[34:35], v[102:103], v[34:35], v[90:91]
	v_pk_fma_f32 v[32:33], v[100:101], v[32:33], v[88:89]
	v_pk_fma_f32 v[30:31], v[106:107], v[30:31], v[86:87]
	v_pk_fma_f32 v[28:29], v[104:105], v[28:29], v[84:85]
	v_pk_fma_f32 v[26:27], v[110:111], v[26:27], v[82:83]
	v_pk_fma_f32 v[24:25], v[108:109], v[24:25], v[80:81]
	v_pk_fma_f32 v[22:23], v[114:115], v[22:23], v[78:79]
	v_pk_fma_f32 v[20:21], v[112:113], v[20:21], v[76:77]
	v_pk_fma_f32 v[18:19], v[118:119], v[18:19], v[74:75]
	v_pk_fma_f32 v[16:17], v[116:117], v[16:17], v[72:73]
	v_pk_fma_f32 v[14:15], v[122:123], v[14:15], v[70:71]
	v_pk_fma_f32 v[12:13], v[120:121], v[12:13], v[68:69]
	v_pk_fma_f32 v[10:11], v[126:127], v[10:11], v[66:67]
	v_pk_fma_f32 v[8:9], v[124:125], v[8:9], v[64:65]
	v_pk_fma_f32 v[6:7], v[130:131], v[6:7], v[98:99]
	v_pk_fma_f32 v[4:5], v[128:129], v[4:5], v[96:97]
	v_cvt_pk_bf16_f32 v32, v32, v33
	v_cvt_pk_bf16_f32 v33, v34, v35
	v_cvt_pk_bf16_f32 v28, v28, v29
	v_cvt_pk_bf16_f32 v29, v30, v31
	v_cvt_pk_bf16_f32 v24, v24, v25
	v_cvt_pk_bf16_f32 v25, v26, v27
	v_cvt_pk_bf16_f32 v20, v20, v21
	v_cvt_pk_bf16_f32 v21, v22, v23
	v_cvt_pk_bf16_f32 v16, v16, v17
	v_cvt_pk_bf16_f32 v17, v18, v19
	v_cvt_pk_bf16_f32 v12, v12, v13
	v_cvt_pk_bf16_f32 v13, v14, v15
	v_cvt_pk_bf16_f32 v8, v8, v9
	v_cvt_pk_bf16_f32 v9, v10, v11
	v_cvt_pk_bf16_f32 v4, v4, v5
	v_cvt_pk_bf16_f32 v5, v6, v7
	flat_store_dwordx2 v[142:143], v[32:33] sc0 sc1
	flat_store_dwordx2 v[142:143], v[28:29] offset:512 sc0 sc1
	flat_store_dwordx2 v[142:143], v[24:25] offset:1024 sc0 sc1
	flat_store_dwordx2 v[142:143], v[20:21] offset:1536 sc0 sc1
	flat_store_dwordx2 v[142:143], v[16:17] offset:2048 sc0 sc1
	flat_store_dwordx2 v[142:143], v[12:13] offset:2560 sc0 sc1
	flat_store_dwordx2 v[142:143], v[8:9] offset:3072 sc0 sc1
	flat_store_dwordx2 v[142:143], v[4:5] offset:3584 sc0 sc1
	v_lshl_add_u64 v[142:143], v[142:143], 0, s[22:23]
	s_and_b64 vcc, exec, s[24:25]
	v_mov_b32_e32 v32, v92
	v_mov_b32_e32 v33, v93
	v_mov_b32_e32 v34, v94
	v_mov_b32_e32 v35, v95
	v_mov_b32_e32 v28, v60
	v_mov_b32_e32 v29, v61
	v_mov_b32_e32 v30, v62
	v_mov_b32_e32 v31, v63
	v_mov_b32_e32 v24, v52
	v_mov_b32_e32 v25, v53
	v_mov_b32_e32 v26, v54
	v_mov_b32_e32 v27, v55
	v_mov_b32_e32 v20, v44
	v_mov_b32_e32 v21, v45
	v_mov_b32_e32 v22, v46
	v_mov_b32_e32 v23, v47
	v_mov_b32_e32 v16, v56
	v_mov_b32_e32 v17, v57
	v_mov_b32_e32 v18, v58
	v_mov_b32_e32 v19, v59
	v_mov_b32_e32 v12, v48
	v_mov_b32_e32 v13, v49
	v_mov_b32_e32 v14, v50
	v_mov_b32_e32 v15, v51
	v_mov_b32_e32 v8, v40
	v_mov_b32_e32 v9, v41
	v_mov_b32_e32 v10, v42
	v_mov_b32_e32 v11, v43
	v_mov_b32_e32 v4, v36
	v_mov_b32_e32 v5, v37
	v_mov_b32_e32 v6, v38
	v_mov_b32_e32 v7, v39
	s_cbranch_vccnz .LBB0_254

; __device__ __forceinline__ unsigned pk2(float lo, float hi) { pk2_f2_t v = {lo, hi}; pk2_b2_t b = __builtin_convertvector(v, pk2_b2_t); return __builtin_bit_cast(unsigned, b); }
; template <int K> __device__ __forceinline__ float lx(float v) { return __builtin_bit_cast(float, lx_i<K>(__builtin_bit_cast(int, v))); }
; __device__ __forceinline__ float half_sum(float v) { unsigned a, b; half_swap(__builtin_bit_cast(unsigned, v), a, b); return __builtin_bit_cast(float, a) + __builtin_bit_cast(float, b); }
; __device__ __forceinline__ float wave_sum(float v) { v += lx<1>(v); v += lx<2>(v); v += lx<4>(v); v += lx<8>(v); v += lx<16>(v); return half_sum(v); }
; __device__ __forceinline__ void norm_mod_rows_b(const bf16* src, const float* gain, const float* sh, const float* sc, bf16* dst, int gw, int NGW, int lane) {
;     ...
;         __builtin_amdgcn_sched_barrier(0);
;         f32x4 x[8];
; #pragma unroll
;         for (int j = 0; j < 4; ++j) { x[2 * j] = (f32x4){lo16(cur[j].x), hi16(cur[j].x), lo16(cur[j].y), hi16(cur[j].y)}; x[2 * j + 1] = (f32x4){lo16(cur[j].z), hi16(cur[j].z), lo16(cur[j].w), hi16(cur[j].w)}; }
;         float ss = 0.f;
; #pragma unroll
;         for (int j = 0; j < 8; ++j) ss += (x[j].x * x[j].x + x[j].y * x[j].y) + (x[j].z * x[j].z + x[j].w * x[j].w);
;         const float rstd = rsqrtf(wave_sum(ss) * (1.f / DM) + 1e-6f);
;         v4u* o16 = (v4u*)(dst + (size_t)m * DM) + lane;
; #pragma unroll
;         for (int j = 0; j < 4; ++j) { const f32x4 y0 = x[2 * j] * rstd * A[2 * j] + B[2 * j], y1 = x[2 * j + 1] * rstd * A[2 * j + 1] + B[2 * j + 1];
;             v4u w; w.x = pk2(y0.x, y0.y); w.y = pk2(y0.z, y0.w); w.z = pk2(y1.x, y1.y); w.w = pk2(y1.z, y1.w); o16[64 * j] = w; }
; #pragma unroll
;         for (int j = 0; j < 4; ++j) cur[j] = nxt[j];
.LBB0_2106:
	v_lshlrev_b32_e32 v110, 16, v32
	v_and_b32_e32 v111, 0xffff0000, v32
	v_lshlrev_b32_e32 v32, 16, v33
	v_and_b32_e32 v33, 0xffff0000, v33
	v_lshlrev_b32_e32 v122, 16, v20
	v_and_b32_e32 v123, 0xffff0000, v20
	v_lshlrev_b32_e32 v124, 16, v21
	v_and_b32_e32 v125, 0xffff0000, v21
	v_mul_f32_e32 v20, v111, v111
	v_mul_f32_e32 v21, v33, v33
	v_lshlrev_b32_e32 v112, 16, v34
	v_and_b32_e32 v113, 0xffff0000, v34
	v_lshlrev_b32_e32 v34, 16, v35
	v_and_b32_e32 v35, 0xffff0000, v35
	v_fmac_f32_e32 v20, v110, v110
	v_fmac_f32_e32 v21, v32, v32
	v_lshlrev_b32_e32 v126, 16, v22
	v_and_b32_e32 v127, 0xffff0000, v22
	v_add_f32_e32 v20, v20, v21
	v_mul_f32_e32 v21, v113, v113
	v_mul_f32_e32 v22, v35, v35
	v_fmac_f32_e32 v21, v112, v112
	v_fmac_f32_e32 v22, v34, v34
	v_lshlrev_b32_e32 v114, 16, v28
	v_and_b32_e32 v115, 0xffff0000, v28
	v_lshlrev_b32_e32 v28, 16, v29
	v_and_b32_e32 v29, 0xffff0000, v29
	v_add_f32_e32 v21, v21, v22
	v_add_f32_e32 v20, v20, v21
	v_mul_f32_e32 v21, v115, v115
	v_mul_f32_e32 v22, v29, v29
	v_fmac_f32_e32 v21, v114, v114
	v_fmac_f32_e32 v22, v28, v28
	v_lshlrev_b32_e32 v116, 16, v30
	v_and_b32_e32 v117, 0xffff0000, v30
	v_lshlrev_b32_e32 v30, 16, v31
	v_and_b32_e32 v31, 0xffff0000, v31
	v_add_f32_e32 v21, v21, v22
	v_add_f32_e32 v20, v20, v21
	v_mul_f32_e32 v21, v117, v117
	v_mul_f32_e32 v22, v31, v31
	v_fmac_f32_e32 v21, v116, v116
	v_fmac_f32_e32 v22, v30, v30
	v_lshlrev_b32_e32 v118, 16, v24
	v_and_b32_e32 v119, 0xffff0000, v24
	v_lshlrev_b32_e32 v24, 16, v25
	v_and_b32_e32 v25, 0xffff0000, v25
	v_add_f32_e32 v21, v21, v22
	v_add_f32_e32 v20, v21, v20
	v_mul_f32_e32 v21, v119, v119
	v_mul_f32_e32 v22, v25, v25
	v_fmac_f32_e32 v21, v118, v118
	v_fmac_f32_e32 v22, v24, v24
	v_lshlrev_b32_e32 v120, 16, v26
	v_and_b32_e32 v121, 0xffff0000, v26
	v_lshlrev_b32_e32 v26, 16, v27
	v_and_b32_e32 v27, 0xffff0000, v27
	v_add_f32_e32 v21, v21, v22
	v_add_f32_e32 v20, v21, v20
	v_mul_f32_e32 v21, v121, v121
	v_mul_f32_e32 v22, v27, v27
	v_fmac_f32_e32 v21, v120, v120
	v_fmac_f32_e32 v22, v26, v26
	v_add_f32_e32 v21, v21, v22
	v_add_f32_e32 v20, v21, v20
	v_mul_f32_e32 v21, v123, v123
	v_mul_f32_e32 v22, v125, v125
	v_fmac_f32_e32 v21, v122, v122
	v_fmac_f32_e32 v22, v124, v124
	v_and_b32_e32 v129, 0xffff0000, v23
	v_add_f32_e32 v21, v21, v22
	v_lshlrev_b32_e32 v128, 16, v23
	v_add_f32_e32 v20, v21, v20
	v_mul_f32_e32 v21, v127, v127
	v_mul_f32_e32 v22, v129, v129
	v_fmac_f32_e32 v21, v126, v126
	v_fmac_f32_e32 v22, v128, v128
	v_add_f32_e32 v21, v21, v22
	v_add_f32_e32 v20, v21, v20
	ds_swizzle_b32 v21, v20 offset:swizzle(SWAP,1)
	s_mov_b32 s3, 0x800000
	s_waitcnt lgkmcnt(0)
	v_add_f32_e32 v20, v20, v21
	ds_swizzle_b32 v21, v20 offset:swizzle(SWAP,2)
	s_waitcnt lgkmcnt(0)
	v_add_f32_e32 v20, v20, v21
	ds_swizzle_b32 v21, v20 offset:swizzle(SWAP,4)
	s_waitcnt lgkmcnt(0)
	v_add_f32_e32 v20, v20, v21
	ds_swizzle_b32 v21, v20 offset:swizzle(SWAP,8)
	s_waitcnt lgkmcnt(0)
	v_add_f32_e32 v20, v20, v21
	ds_swizzle_b32 v21, v20 offset:swizzle(SWAP,16)
	s_waitcnt lgkmcnt(0)
	v_add_f32_e32 v20, v20, v21
	v_mov_b32_e32 v21, v20
	s_nop 1
	v_permlane32_swap_b32_e32 v20, v21
	v_add_f32_e32 v20, v20, v21
	v_fmamk_f32 v20, v20, 0x3a000000, v228
	v_mul_f32_e32 v21, 0x4b800000, v20
	v_cmp_gt_f32_e32 vcc, s3, v20
	s_nop 1
	v_cndmask_b32_e32 v20, v20, v21, vcc
	v_rsq_f32_e32 v20, v20
	s_nop 0
	v_mul_f32_e32 v21, 0x45800000, v20
	v_cndmask_b32_e32 v130, v20, v21, vcc
	v_pk_mul_f32 v[20:21], v[110:111], v[130:131] op_sel_hi:[1,0]
	v_pk_mul_f32 v[22:23], v[32:33], v[130:131] op_sel_hi:[1,0]
	v_pk_mul_f32 v[32:33], v[112:113], v[130:131] op_sel_hi:[1,0]
	v_pk_mul_f32 v[34:35], v[34:35], v[130:131] op_sel_hi:[1,0]
	s_waitcnt vmcnt(0)
	v_pk_fma_f32 v[22:23], v[70:71], v[22:23], v[58:59]
	v_pk_fma_f32 v[20:21], v[68:69], v[20:21], v[56:57]
	v_pk_fma_f32 v[34:35], v[74:75], v[34:35], v[46:47]
	v_pk_fma_f32 v[32:33], v[72:73], v[32:33], v[44:45]
	v_cvt_pk_bf16_f32 v20, v20, v21
	v_cvt_pk_bf16_f32 v21, v22, v23
	v_cvt_pk_bf16_f32 v22, v32, v33
	v_cvt_pk_bf16_f32 v23, v34, v35
	flat_store_dwordx4 v[106:107], v[20:23] sc0 sc1
	v_pk_mul_f32 v[30:31], v[30:31], v[130:131] op_sel_hi:[1,0]
	v_pk_mul_f32 v[26:27], v[26:27], v[130:131] op_sel_hi:[1,0]
	v_pk_mul_f32 v[20:21], v[114:115], v[130:131] op_sel_hi:[1,0]
	v_pk_mul_f32 v[22:23], v[28:29], v[130:131] op_sel_hi:[1,0]
	v_pk_mul_f32 v[28:29], v[116:117], v[130:131] op_sel_hi:[1,0]
	s_waitcnt vmcnt(0)
	v_pk_fma_f32 v[22:23], v[78:79], v[22:23], v[54:55]
	v_pk_fma_f32 v[20:21], v[76:77], v[20:21], v[52:53]
	v_pk_fma_f32 v[30:31], v[82:83], v[30:31], v[42:43]
	v_pk_fma_f32 v[28:29], v[80:81], v[28:29], v[40:41]
	v_cvt_pk_bf16_f32 v20, v20, v21
	v_cvt_pk_bf16_f32 v21, v22, v23
	v_cvt_pk_bf16_f32 v22, v28, v29
	v_cvt_pk_bf16_f32 v23, v30, v31
	flat_store_dwordx4 v[106:107], v[20:23] offset:1024 sc0 sc1
	v_pk_fma_f32 v[26:27], v[90:91], v[26:27], v[38:39]
	v_mov_b64_e32 v[34:35], v[6:7]
	v_pk_mul_f32 v[20:21], v[118:119], v[130:131] op_sel_hi:[1,0]
	v_pk_mul_f32 v[22:23], v[24:25], v[130:131] op_sel_hi:[1,0]
	v_pk_mul_f32 v[24:25], v[120:121], v[130:131] op_sel_hi:[1,0]
	v_pk_fma_f32 v[22:23], v[86:87], v[22:23], v[50:51]
	v_pk_fma_f32 v[20:21], v[84:85], v[20:21], v[48:49]
	v_pk_fma_f32 v[24:25], v[88:89], v[24:25], v[36:37]
	v_cvt_pk_bf16_f32 v20, v20, v21
	v_cvt_pk_bf16_f32 v21, v22, v23
	v_cvt_pk_bf16_f32 v22, v24, v25
	v_cvt_pk_bf16_f32 v23, v26, v27
	flat_store_dwordx4 v[106:107], v[20:23] offset:2048 sc0 sc1
	v_pk_mul_f32 v[24:25], v[126:127], v[130:131] op_sel_hi:[1,0]
	v_pk_mul_f32 v[26:27], v[128:129], v[130:131] op_sel_hi:[1,0]
	v_pk_mul_f32 v[20:21], v[122:123], v[130:131] op_sel_hi:[1,0]
	v_pk_mul_f32 v[22:23], v[124:125], v[130:131] op_sel_hi:[1,0]
	v_pk_fma_f32 v[20:21], v[92:93], v[20:21], v[64:65]
	v_pk_fma_f32 v[22:23], v[94:95], v[22:23], v[66:67]
	v_pk_fma_f32 v[26:27], v[98:99], v[26:27], v[62:63]
	v_pk_fma_f32 v[24:25], v[96:97], v[24:25], v[60:61]
	v_cvt_pk_bf16_f32 v20, v20, v21
	v_cvt_pk_bf16_f32 v21, v22, v23
	v_cvt_pk_bf16_f32 v22, v24, v25
	v_cvt_pk_bf16_f32 v23, v26, v27
	flat_store_dwordx4 v[106:107], v[20:23] offset:3072 sc0 sc1
	v_mov_b64_e32 v[30:31], v[10:11]
	v_mov_b64_e32 v[26:27], v[14:15]
	v_mov_b64_e32 v[22:23], v[18:19]
	v_lshl_add_u64 v[106:107], v[106:107], 0, s[16:17]
	s_andn2_b64 vcc, exec, s[20:21]
	v_mov_b64_e32 v[32:33], v[4:5]
	v_mov_b64_e32 v[28:29], v[8:9]
	v_mov_b64_e32 v[24:25], v[12:13]
	v_mov_b64_e32 v[20:21], v[16:17]
	s_cbranch_vccz .LBB0_2109
